# v052 minus the per-tile conditional s_setprio block (no effect on arbitration) and minus one scalar copy at the STEP start
# speedup vs baseline: 1.0050x; 1.0050x over previous
; #define LAS __attribute__((address_space(3)))
; __global__ void __launch_bounds__(NWAVES * 64, 2) mk_fwd(Args a_unused) {
;     extern __shared__ __attribute__((aligned(16))) unsigned char lds[];
;     cg::grid_group grid = cg::this_grid();
;     const int tid = threadIdx.x, lane = tid & 63, wave = __builtin_amdgcn_readfirstlane(tid >> 6);
;     const int G = gridDim.x, bx = blockIdx.x;
;     const int vcu = (G % 8 == 0) ? (bx % 8) * (G / 8) + bx / 8 : bx;
;     ...
;     LAS unsigned char* ldsl = (LAS unsigned char*)lds;
;     volatile LAS unsigned* bst = (volatile LAS unsigned*)(ldsl + LDS_BYTES - 16);
;     if (tid < 2) bst[tid] = 0u;
;     __syncthreads();
_Z6mk_fwd4Args:
	s_load_dwordx2 s[24:25], s[0:1], 0xa0
	s_add_u32 s6, s0, 0xa0
	s_addc_u32 s7, s1, 0
	v_and_b32_e32 v164, 0x3ff, v0
	s_mov_b32 s33, s2
	s_waitcnt lgkmcnt(0)
	s_and_b32 s3, s24, 7
	v_readfirstlane_b32 s8, v164
	s_cmp_lg_u32 s3, 0
	s_cbranch_scc0 .LBB0_9
	s_load_dword s3, s[0:1], 0xa8
	v_cmp_gt_u32_e32 vcc, 2, v164
	s_and_saveexec_b64 s[4:5], vcc

; __device__ __forceinline__ void finishSM(f32x16& p0, f32x16& p1, float alpha, float& l_reg, bf16x8& pa0, bf16x8& pa1, bf16x8& pa2, bf16x8& pa3) {
; #pragma unroll
;   for (int r = 0; r < 16; ++r) p1[r] = __builtin_amdgcn_exp2f(p1[r]);
;   float ps = 0;
; #pragma unroll
;   for (int r = 0; r < 16; ++r) ps += p0[r];
; #pragma unroll
;   for (int r = 0; r < 16; ++r) ps += p1[r];
;   { auto rr = __builtin_amdgcn_permlane32_swap(__float_as_uint(ps), __float_as_uint(ps), false, false);
;     ps = __uint_as_float(rr[0]) + __uint_as_float(rr[1]); }
;   l_reg = l_reg * alpha + ps;
;     ...
;   PK4(p0, 0, pa0); PK4(p0, 8, pa1); PK4(p1, 0, pa2); PK4(p1, 8, pa3);
;     ...
; }
; template <int NQ> __device__ __forceinline__ void qkt(f32x16& p0, f32x16& p1, const char* Ks, const bf16x8* qr, int r32, int hi, int kcolB) {
;   p0 = f32x16{}; p1 = f32x16{};
; #pragma unroll
;   for (int d0 = 0; d0 < NQ; ++d0) { const int cb = kcolB + (d0 * 16 + hi * 8) * 2;
;     bf16x8 b0 = *reinterpret_cast<const bf16x8*>(Ks + KSWZ(r32, cb));
;     bf16x8 b1 = *reinterpret_cast<const bf16x8*>(Ks + KSWZ(32 + r32, cb));
;     p0 = __builtin_amdgcn_mfma_f32_32x32x16_bf16(b0, qr[d0], p0, 0, 0, 0);
;     p1 = __builtin_amdgcn_mfma_f32_32x32x16_bf16(b1, qr[d0], p1, 0, 0, 0); }
; }
; __device__ __forceinline__ void qkt0(f32x16& p0, f32x16& p1, const char* Ks, const char* Qs, int r32, int hi, int kcolB, const f32x16& init) {
; #pragma unroll
;   for (int d0 = 0; d0 < 4; ++d0) { const int cb = kcolB + (d0 * 16 + hi * 8) * 2;
;     bf16x8 b0 = *reinterpret_cast<const bf16x8*>(Ks + KSWZ(r32, cb));
;     bf16x8 b1 = *reinterpret_cast<const bf16x8*>(Ks + KSWZ(32 + r32, cb));
;     bf16x8 qf = *reinterpret_cast<const bf16x8*>(Qs + r32 * 128 + (((2 * d0 + hi) ^ (r32 & 7)) << 4));
;     if (d0 == 0) { p0 = __builtin_amdgcn_mfma_f32_32x32x16_bf16(b0, qf, init, 0, 0, 0); p1 = __builtin_amdgcn_mfma_f32_32x32x16_bf16(b1, qf, init, 0, 0, 0); }
;     else { p0 = __builtin_amdgcn_mfma_f32_32x32x16_bf16(b0, qf, p0, 0, 0, 0); p1 = __builtin_amdgcn_mfma_f32_32x32x16_bf16(b1, qf, p1, 0, 0, 0); } }
; }
.LBB0_215:
	v_add_u32_e32 v112, s59, v193
	v_add_u32_e32 v116, s59, v194
	ds_read_b128 v[112:115], v112 offset:16384
	ds_read_b128 v[202:205], v181
	ds_read_b128 v[206:209], v180
	ds_read_b128 v[210:213], v116 offset:16384
	v_exp_f32_e32 v234, v96
	v_add_f32_e32 v96, 0, v161
	s_waitcnt lgkmcnt(2)
	v_mfma_f32_32x32x16_bf16 v[128:143], v[112:115], v[202:205], v[80:95]
	v_add_u32_e32 v112, s59, v197
	v_add_u32_e32 v113, s59, v195
	v_add_f32_e32 v96, v163, v96
	ds_read_b128 v[214:217], v112 offset:16384
	ds_read_b128 v[218:221], v113 offset:16384
	v_add_f32_e32 v96, v159, v96
	v_add_f32_e32 v96, v162, v96
	v_add_f32_e32 v96, v157, v96
	s_waitcnt lgkmcnt(2)
	v_mfma_f32_32x32x16_bf16 v[112:127], v[210:213], v[202:205], v[80:95]
	v_add_f32_e32 v96, v160, v96
	v_add_f32_e32 v96, v156, v96
	v_add_f32_e32 v96, v158, v96
	v_add_f32_e32 v96, v153, v96
	v_add_f32_e32 v96, v155, v96
	v_add_f32_e32 v96, v151, v96
	v_add_f32_e32 v96, v154, v96
	s_waitcnt lgkmcnt(0)
	v_mfma_f32_32x32x16_bf16 v[128:143], v[218:221], v[206:209], v[128:143]
	v_add_f32_e32 v96, v149, v96
	v_add_u32_e32 v201, s59, v199
	v_add_u32_e32 v210, s59, v196
	v_exp_f32_e32 v235, v97
	v_add_f32_e32 v96, v152, v96
	ds_read_b128 v[202:205], v201 offset:16384
	ds_read_b128 v[210:213], v210 offset:16384
	ds_read_b128 v[222:225], v179
	ds_read_b128 v[226:229], v178
	v_exp_f32_e32 v236, v98
	v_mfma_f32_32x32x16_bf16 v[112:127], v[214:217], v[206:209], v[112:127]
	v_add_f32_e32 v96, v148, v96
	v_exp_f32_e32 v237, v99
	v_add_f32_e32 v96, v150, v96
	v_exp_f32_e32 v238, v100
	v_add_f32_e32 v96, v234, v96
	v_exp_f32_e32 v239, v101
	v_add_f32_e32 v96, v235, v96
	v_exp_f32_e32 v206, v102
	s_waitcnt lgkmcnt(1)
	v_mfma_f32_32x32x16_bf16 v[128:143], v[210:213], v[222:225], v[128:143]
	v_add_f32_e32 v96, v236, v96
	v_exp_f32_e32 v207, v103
	v_add_f32_e32 v96, v237, v96
	v_add_u32_e32 v201, s59, v200
	v_add_u32_e32 v230, s59, v198
	v_exp_f32_e32 v208, v104
	v_add_f32_e32 v96, v238, v96
	v_mfma_f32_32x32x16_bf16 v[112:127], v[202:205], v[222:225], v[112:127]
	ds_read_b128 v[218:221], v201 offset:16384
	ds_read_b128 v[230:233], v230 offset:16384
	v_exp_f32_e32 v209, v105
	v_add_f32_e32 v96, v239, v96
	v_exp_f32_e32 v214, v106
	v_add_f32_e32 v96, v206, v96
	v_exp_f32_e32 v215, v107
	v_add_f32_e32 v96, v207, v96
	v_exp_f32_e32 v216, v108
	v_add_f32_e32 v96, v208, v96
	v_exp_f32_e32 v210, v109
	v_add_f32_e32 v96, v209, v96
	v_exp_f32_e32 v211, v110
	s_waitcnt lgkmcnt(0)
	v_mfma_f32_32x32x16_bf16 v[128:143], v[230:233], v[226:229], v[128:143]
	v_add_f32_e32 v96, v214, v96
	v_exp_f32_e32 v111, v111
	v_add_f32_e32 v96, v215, v96
	v_add_f32_e32 v96, v216, v96
	v_add_f32_e32 v96, v210, v96
	v_add_f32_e32 v96, v211, v96
	v_add_f32_e32 v201, v111, v96
	v_mfma_f32_32x32x16_bf16 v[112:127], v[218:221], v[226:229], v[112:127]
	v_mov_b32_e32 v202, v201
	s_nop 1
	v_permlane32_swap_b32_e32 v201, v202
	v_cvt_pk_bf16_f32 v96, v161, v163
	v_cvt_pk_bf16_f32 v97, v159, v162
	v_cvt_pk_bf16_f32 v98, v157, v160
	v_cvt_pk_bf16_f32 v99, v156, v158
	v_cvt_pk_bf16_f32 v100, v153, v155
	v_cvt_pk_bf16_f32 v101, v151, v154
	v_cvt_pk_bf16_f32 v102, v149, v152
	v_cvt_pk_bf16_f32 v103, v148, v150
	v_cvt_pk_bf16_f32 v104, v234, v235
	v_cvt_pk_bf16_f32 v105, v236, v237
	v_cvt_pk_bf16_f32 v106, v238, v239
	v_cvt_pk_bf16_f32 v107, v206, v207
	v_cvt_pk_bf16_f32 v108, v208, v209
	v_cvt_pk_bf16_f32 v109, v214, v215
	v_cvt_pk_bf16_f32 v110, v216, v210
	v_cvt_pk_bf16_f32 v111, v211, v111
	s_nop 0
	v_permlane32_swap_b32_e32 v96, v98
	v_permlane32_swap_b32_e32 v97, v99
	v_permlane32_swap_b32_e32 v100, v102
	v_permlane32_swap_b32_e32 v101, v103
	v_permlane32_swap_b32_e32 v104, v106
	v_permlane32_swap_b32_e32 v105, v107
	v_permlane32_swap_b32_e32 v108, v110
	v_permlane32_swap_b32_e32 v109, v111
	v_add_u32_e32 v203, s36, v175
	ds_read_b64_tr_b16 v[148:149], v203 offset:0
	ds_read_b64_tr_b16 v[150:151], v203 offset:0x800
	ds_read_b64_tr_b16 v[152:153], v203 offset:0x1000
	ds_read_b64_tr_b16 v[154:155], v203 offset:0x1800
	ds_read_b64_tr_b16 v[156:157], v203 offset:0x2000
	ds_read_b64_tr_b16 v[158:159], v203 offset:0x2800
	ds_read_b64_tr_b16 v[160:161], v203 offset:0x3000
	ds_read_b64_tr_b16 v[162:163], v203 offset:0x3800
	s_add_i32 s34, s58, 1
	s_waitcnt lgkmcnt(0)
; __device__ __forceinline__ void pv_d0(f32x16* o, int vb, bf16x8 pa0, bf16x8 pa1, bf16x8 pa2, bf16x8 pa3) {
;   s16x4 la[4], ha[4];
;   rd8<0>(la, ha, vb); WAITDEP(0, la, ha); mma4(o[0], la, ha, pa0, pa1, pa2, pa3);
;   rd8<1>(la, ha, vb); WAITDEP(0, la, ha); mma4(o[1], la, ha, pa0, pa1, pa2, pa3);
;   rd8<2>(la, ha, vb); WAITDEP(0, la, ha); mma4(o[2], la, ha, pa0, pa1, pa2, pa3);
;   rd8<3>(la, ha, vb); WAITDEP(0, la, ha); mma4(o[3], la, ha, pa0, pa1, pa2, pa3);
; }
; template <int MODE>
; __device__ __forceinline__ void attn_unit(bf16r* P0, const bf16r* __restrict__ PKV, int rowbase, int seqL, int h, int blk, float lam,
;                                           const float* __restrict__ subg, const float* __restrict__ tsrc, char* lds) {
;   constexpr int NQ = (MODE == 0) ? 4 : 8;
;   int tid_ = threadIdx.x; asm volatile("" : "+v"(tid_));
;   const int tid = tid_, wid = __builtin_amdgcn_readfirstlane(tid >> 6), lane = tid & 63, r32 = lane & 31, hi = lane >> 5;
;   float* ws = (float*)(lds + OFF_WS) + wid * 64; float* li_l = ws; float* al_l = ws + 32;
;   float* tb = (float*)(lds + OFF_TB);
;   int qrow, kcolB, tbase, NT, colbase, gr = 0, rs = 0, qc = 0, cmap = 0;
;   float bL = 0.f, bR = 0.f;
;   if constexpr (MODE == 0) {
;     cmap = wid >> 2; qrow = blk * 128 + (wid & 3) * 32; kcolB = cmap * 128; tbase = 0; NT = seqL / KVBLK; colbase = h * 128;
;     bL = tsrc[15 * 8 + h] * LOG2E; bR = tsrc[31 * 8 + h] * LOG2E;
;     { const int rel = tid - 256, n = rel < 0 ? -rel : rel;
;       int bk = n < 8 ? n : min(15, 8 + (31 - __clz((n * n) >> 6))); if (rel > 0) bk += 16;
;       tb[tid] = tsrc[bk * 8 + h] * LOG2E; }
;   } else {
;     const int rows = seqL / 64; qrow = blk * 256 + wid * 32; kcolB = 0; colbase = 1024 + h * 128; NT = 12;
;     const int rs0 = min(max(blk * 4 - 4, 0), rows - 8); tbase = min(rs0, rows - 12);
;     gr = blk * 4 + (wid >> 1); rs = min(max(gr - 4, 0), rows - 8); qc = (wid & 1) * 32 + r32;
;     for (int i = tid; i < 15 * 128; i += 512) { const int dr = i >> 7, dc = (i & 127) - 48; tb[i] = (dc >= 0 && dc < 31) ? tsrc[(h * 15 + dr) * 31 + dc] * LOG2E : 0.f; }
;   }
;   const bf16r* Qw = P0 + (size_t)(rowbase + qrow + r32) * LD + colbase + (MODE == 0 ? cmap * 64 : 0) + hi * 8;
;   const bf16r* Kh = PKV + (size_t)rowbase * LD + h * 128; const bf16r* Vh = Kh + 1024;
;   float m_reg = -1e30f, l_reg = 0; f32x16 o[4] = {};
	s_add_i32 s60, s37, 0
	v_mfma_f32_32x32x16_bf16 v[64:79], v[96:99], v[148:151], v[64:79]
	ds_read_b64_tr_b16 v[148:149], v203 offset:0x200
	ds_read_b64_tr_b16 v[150:151], v203 offset:0xa00
	ds_read_b64_tr_b16 v[204:205], v203 offset:0x1200
	ds_read_b64_tr_b16 v[206:207], v203 offset:0x1a00
	ds_read_b64_tr_b16 v[208:209], v203 offset:0x2200
	ds_read_b64_tr_b16 v[210:211], v203 offset:0x2a00
	ds_read_b64_tr_b16 v[212:213], v203 offset:0x3200
	v_mfma_f32_32x32x16_bf16 v[64:79], v[100:103], v[152:155], v[64:79]
	ds_read_b64_tr_b16 v[214:215], v203 offset:0x3a00
	s_min_i32 s34, s34, s39
	s_waitcnt lgkmcnt(0)
	s_cmp_ge_i32 s34, s56
	s_cselect_b32 s35, s57, 0
	s_add_i32 s35, s35, s34
	s_lshl_b32 s34, s35, 6
	v_mfma_f32_32x32x16_bf16 v[64:79], v[104:107], v[156:159], v[64:79]
	v_mfma_f32_32x32x16_bf16 v[48:63], v[96:99], v[148:151], v[48:63]
	ds_read_b64_tr_b16 v[148:149], v203 offset:0x400
	ds_read_b64_tr_b16 v[150:151], v203 offset:0xc00
	ds_read_b64_tr_b16 v[152:153], v203 offset:0x1400
	ds_read_b64_tr_b16 v[154:155], v203 offset:0x1c00
	v_mfma_f32_32x32x16_bf16 v[64:79], v[108:111], v[160:163], v[64:79]
	ds_read_b64_tr_b16 v[160:161], v203 offset:0x2400
	ds_read_b64_tr_b16 v[162:163], v203 offset:0x2c00
	v_mfma_f32_32x32x16_bf16 v[48:63], v[100:103], v[204:207], v[48:63]
	ds_read_b64_tr_b16 v[204:205], v203 offset:0x3400
	ds_read_b64_tr_b16 v[206:207], v203 offset:0x3c00
	s_nop 0
	s_waitcnt lgkmcnt(0)
	ds_read_b64_tr_b16 v[216:217], v203 offset:0x600
	ds_read_b64_tr_b16 v[218:219], v203 offset:0xe00
	s_nop 0
	v_mfma_f32_32x32x16_bf16 v[32:47], v[96:99], v[148:151], v[32:47]
	s_lshl_b32 s98, s34, 12
	s_add_u32 s98, s30, s98
	s_addc_u32 s99, s31, 0
	v_mfma_f32_32x32x16_bf16 v[48:63], v[104:107], v[208:211], v[48:63]
	ds_read_b64_tr_b16 v[208:209], v203 offset:0x1600
	ds_read_b64_tr_b16 v[210:211], v203 offset:0x1e00
	ds_read_b64_tr_b16 v[220:221], v203 offset:0x2600
	ds_read_b64_tr_b16 v[222:223], v203 offset:0x2e00
	ds_read_b64_tr_b16 v[224:225], v203 offset:0x3600
	ds_read_b64_tr_b16 v[226:227], v203 offset:0x3e00
	v_mfma_f32_32x32x16_bf16 v[32:47], v[100:103], v[152:155], v[32:47]
	s_waitcnt lgkmcnt(0)
	s_waitcnt vmcnt(0)
	global_load_dwordx4 v[156:159], v252, s[98:99] offset:2048
	s_nop 0
	global_load_dwordx4 v[148:151], v252, s[98:99]
	v_add_u32_e32 v203, s60, v183
	v_mfma_f32_32x32x16_bf16 v[32:47], v[104:107], v[160:163], v[32:47]
	global_load_dwordx4 v[160:163], v253, s[98:99] offset:2048
	s_nop 0
	global_load_dwordx4 v[152:155], v253, s[98:99]
	ds_write_b128 v203, v[6:9]
	v_add_u32_e32 v6, s60, v189
	ds_write_b128 v6, v[144:147]
	v_add_u32_e32 v6, s60, v190
	ds_write_b128 v6, v[2:5] offset:16384
	v_add_u32_e32 v2, s60, v191
	v_mfma_f32_32x32x16_bf16 v[16:31], v[96:99], v[216:219], v[16:31]
	ds_write_b128 v2, v[10:13] offset:16384
	v_max_f32_e32 v2, v128, v129
	v_max3_f32 v2, v2, v130, v131
	v_max3_f32 v2, v2, v132, v133
	v_max3_f32 v2, v2, v134, v135
	v_mfma_f32_32x32x16_bf16 v[16:31], v[100:103], v[208:211], v[16:31]
	v_max3_f32 v2, v2, v136, v137
	v_max3_f32 v2, v2, v138, v139
	v_max3_f32 v2, v2, v140, v141
	v_max3_f32 v2, v2, v142, v143
	v_max3_f32 v2, v2, v112, v113
	v_max3_f32 v2, v2, v114, v115
	v_max3_f32 v2, v2, v116, v117
	v_mfma_f32_32x32x16_bf16 v[16:31], v[104:107], v[220:223], v[16:31]
	v_max3_f32 v2, v2, v118, v119
	v_max3_f32 v2, v2, v120, v121
	v_max3_f32 v2, v2, v122, v123
	v_max3_f32 v2, v2, v124, v125
	v_max3_f32 v2, v2, v126, v127
	v_mov_b32_e32 v3, v2
	s_nop 1
	v_permlane32_swap_b32_e32 v2, v3
	v_mfma_f32_32x32x16_bf16 v[48:63], v[108:111], v[212:215], v[48:63]
	v_max_f32_e32 v2, v2, v3
	v_cmp_ge_f32_e32 vcc, s49, v2
	s_cmp_eq_u64 vcc, exec
	v_mov_b32_e32 v203, 1.0
	v_mfma_f32_32x32x16_bf16 v[32:47], v[108:111], v[204:207], v[32:47]
	v_mfma_f32_32x32x16_bf16 v[16:31], v[108:111], v[224:227], v[16:31]
	s_cbranch_scc0 .LBB0_229
	s_branch .LBB0_220

; __device__ __forceinline__ void finishSM(f32x16& p0, f32x16& p1, float alpha, float& l_reg, bf16x8& pa0, bf16x8& pa1, bf16x8& pa2, bf16x8& pa3) {
; #pragma unroll
;   for (int r = 0; r < 16; ++r) p1[r] = __builtin_amdgcn_exp2f(p1[r]);
;   float ps = 0;
; #pragma unroll
;   for (int r = 0; r < 16; ++r) ps += p0[r];
; #pragma unroll
;   for (int r = 0; r < 16; ++r) ps += p1[r];
;   { auto rr = __builtin_amdgcn_permlane32_swap(__float_as_uint(ps), __float_as_uint(ps), false, false);
;     ps = __uint_as_float(rr[0]) + __uint_as_float(rr[1]); }
;   l_reg = l_reg * alpha + ps;
;     ...
;   PK4(p0, 0, pa0); PK4(p0, 8, pa1); PK4(p1, 0, pa2); PK4(p1, 8, pa3);
;     ...
; }
; template <int NQ> __device__ __forceinline__ void qkt(f32x16& p0, f32x16& p1, const char* Ks, const bf16x8* qr, int r32, int hi, int kcolB) {
;   p0 = f32x16{}; p1 = f32x16{};
; #pragma unroll
;   for (int d0 = 0; d0 < NQ; ++d0) { const int cb = kcolB + (d0 * 16 + hi * 8) * 2;
;     bf16x8 b0 = *reinterpret_cast<const bf16x8*>(Ks + KSWZ(r32, cb));
;     bf16x8 b1 = *reinterpret_cast<const bf16x8*>(Ks + KSWZ(32 + r32, cb));
;     p0 = __builtin_amdgcn_mfma_f32_32x32x16_bf16(b0, qr[d0], p0, 0, 0, 0);
;     p1 = __builtin_amdgcn_mfma_f32_32x32x16_bf16(b1, qr[d0], p1, 0, 0, 0); }
; }
; __device__ __forceinline__ void qkt0(f32x16& p0, f32x16& p1, const char* Ks, const char* Qs, int r32, int hi, int kcolB, const f32x16& init) {
; #pragma unroll
;   for (int d0 = 0; d0 < 4; ++d0) { const int cb = kcolB + (d0 * 16 + hi * 8) * 2;
;     bf16x8 b0 = *reinterpret_cast<const bf16x8*>(Ks + KSWZ(r32, cb));
;     bf16x8 b1 = *reinterpret_cast<const bf16x8*>(Ks + KSWZ(32 + r32, cb));
;     bf16x8 qf = *reinterpret_cast<const bf16x8*>(Qs + r32 * 128 + (((2 * d0 + hi) ^ (r32 & 7)) << 4));
; template <int MODE>
; __device__ __forceinline__ void attn_unit(bf16r* P0, const bf16r* __restrict__ PKV, int rowbase, int seqL, int h, int blk, float lam,
;                                           const float* __restrict__ subg, const float* __restrict__ tsrc, char* lds) {
;     ...
;     { const float nv_ = CB(0) - m_reg; _Pragma("unroll") for (int r = 0; r < 16; ++r) negm[r] = nv_; asm volatile("" : "+v"(negm)); }
;     qkt0(pA0, pA1, lds + SLOT_K, Qs, r32, hi, kcolB, negm); scoreConst(pA0, pA1, m_reg, alA);
;     int sPrev = 0, sCur = SLOT, sNext = 2 * SLOT;
.LBB0_220:
	s_cmp_lt_u32 s58, s56
	s_cselect_b64 vcc, -1, 0
	v_cndmask_b32_e32 v2, v15, v14, vcc
	v_sub_f32_e32 v96, v2, v192
	v_cmp_neq_f32_e32 vcc, v96, v80
	s_waitcnt lgkmcnt(0)
	s_barrier
	s_cbranch_vccz .LBB0_222
	v_mov_b32_e32 v97, v96
	v_mov_b32_e32 v98, v96
	v_mov_b32_e32 v99, v96
	v_mov_b32_e32 v100, v96
	v_mov_b32_e32 v101, v96
	v_mov_b32_e32 v102, v96
	v_mov_b32_e32 v103, v96
	v_mov_b32_e32 v104, v96
	v_mov_b32_e32 v105, v96
	v_mov_b32_e32 v106, v96
	v_mov_b32_e32 v107, v96
	v_mov_b32_e32 v108, v96
	v_mov_b32_e32 v109, v96
	v_mov_b32_e32 v110, v96
	v_mov_b32_e32 v111, v96
	s_nop 0
	v_mov_b64_e32 v[80:81], v[96:97]
	v_mov_b64_e32 v[82:83], v[98:99]
	v_mov_b64_e32 v[84:85], v[100:101]
	v_mov_b64_e32 v[86:87], v[102:103]
	v_mov_b64_e32 v[88:89], v[104:105]
	v_mov_b64_e32 v[90:91], v[106:107]
	v_mov_b64_e32 v[92:93], v[108:109]
	v_mov_b64_e32 v[94:95], v[110:111]
.LBB0_222:
	v_exp_f32_e32 v224, v128
	v_exp_f32_e32 v225, v129
	v_exp_f32_e32 v226, v130
	v_exp_f32_e32 v227, v131
	v_exp_f32_e32 v228, v132
	v_exp_f32_e32 v229, v133
	v_exp_f32_e32 v230, v134
	v_exp_f32_e32 v231, v135
	v_exp_f32_e32 v232, v136
	v_exp_f32_e32 v233, v137
	v_exp_f32_e32 v234, v138
	v_exp_f32_e32 v235, v139
	v_exp_f32_e32 v236, v140
	v_exp_f32_e32 v237, v141
	v_exp_f32_e32 v238, v142
	v_exp_f32_e32 v239, v143
	v_add_u32_e32 v2, s60, v193
	ds_read_b128 v[2:5], v2 offset:16384
	ds_read_b128 v[6:9], v181
	v_add_u32_e32 v96, s60, v194
	ds_read_b128 v[10:13], v180
	v_add_u32_e32 v97, s60, v195
	v_add_u32_e32 v208, s60, v199
	s_waitcnt lgkmcnt(1)
	v_mfma_f32_32x32x16_bf16 v[128:143], v[2:5], v[6:9], v[80:95]
	ds_read_b128 v[2:5], v96 offset:16384
	v_add_u32_e32 v96, s60, v197
	ds_read_b128 v[144:147], v96 offset:16384
	ds_read_b128 v[204:207], v97 offset:16384
	v_add_u32_e32 v209, s60, v196
	v_exp_f32_e32 v240, v114
	v_exp_f32_e32 v241, v115
	v_exp_f32_e32 v242, v116
	s_waitcnt lgkmcnt(0)
	v_mfma_f32_32x32x16_bf16 v[128:143], v[204:207], v[10:13], v[128:143]
	v_exp_f32_e32 v206, v112
	v_exp_f32_e32 v207, v113
	v_exp_f32_e32 v243, v117
	v_exp_f32_e32 v244, v118
	v_add_u32_e32 v216, s60, v200
	v_add_u32_e32 v220, s60, v198
	v_mfma_f32_32x32x16_bf16 v[96:111], v[2:5], v[6:9], v[80:95]
	ds_read_b128 v[2:5], v208 offset:16384
	ds_read_b128 v[6:9], v209 offset:16384
	ds_read_b128 v[208:211], v179
	ds_read_b128 v[212:215], v178
	ds_read_b128 v[216:219], v216 offset:16384
	ds_read_b128 v[220:223], v220 offset:16384
	v_cvt_pk_bf16_f32 v116, v224, v225
	v_cvt_pk_bf16_f32 v117, v226, v227
	v_cvt_pk_bf16_f32 v118, v228, v229
	s_nop 0
	v_permlane32_swap_b32_e32 v116, v118
	v_mfma_f32_32x32x16_bf16 v[96:111], v[144:147], v[10:13], v[96:111]
	v_exp_f32_e32 v10, v119
	v_exp_f32_e32 v11, v120
	v_exp_f32_e32 v12, v121
	v_exp_f32_e32 v13, v122
	v_exp_f32_e32 v144, v123
	v_exp_f32_e32 v145, v124
	v_exp_f32_e32 v146, v125
	s_waitcnt lgkmcnt(3)
	v_mfma_f32_32x32x16_bf16 v[128:143], v[6:9], v[208:211], v[128:143]
	v_add_f32_e32 v8, 0, v224
	v_add_f32_e32 v8, v225, v8
	v_add_f32_e32 v8, v226, v8
	v_add_f32_e32 v8, v227, v8
	v_add_f32_e32 v8, v228, v8
	v_exp_f32_e32 v6, v126
	v_exp_f32_e32 v7, v127
	v_mfma_f32_32x32x16_bf16 v[96:111], v[2:5], v[208:211], v[96:111]
	v_add_f32_e32 v2, v229, v8
	v_add_f32_e32 v2, v230, v2
	v_add_f32_e32 v2, v231, v2
	v_add_f32_e32 v2, v232, v2
	v_add_f32_e32 v2, v233, v2
	v_add_f32_e32 v2, v234, v2
	v_add_f32_e32 v2, v235, v2
	v_add_f32_e32 v2, v236, v2
	v_add_f32_e32 v2, v237, v2
	v_add_f32_e32 v2, v238, v2
	v_add_f32_e32 v2, v239, v2
	v_add_f32_e32 v2, v206, v2
	v_add_f32_e32 v2, v207, v2
	v_add_f32_e32 v2, v240, v2
	v_add_f32_e32 v2, v241, v2
	v_add_f32_e32 v2, v242, v2
	v_add_f32_e32 v2, v243, v2
	v_add_f32_e32 v2, v244, v2
	v_add_f32_e32 v2, v10, v2
	v_add_f32_e32 v2, v11, v2
	v_add_f32_e32 v2, v12, v2
	s_waitcnt lgkmcnt(0)
	v_mfma_f32_32x32x16_bf16 v[128:143], v[220:223], v[212:215], v[128:143]
	v_add_f32_e32 v2, v13, v2
	v_add_f32_e32 v2, v144, v2
	v_add_f32_e32 v2, v145, v2
	v_add_f32_e32 v2, v146, v2
	v_add_f32_e32 v2, v6, v2
	v_add_f32_e32 v204, v7, v2
	v_mov_b32_e32 v205, v204
	v_mfma_f32_32x32x16_bf16 v[96:111], v[216:219], v[212:215], v[96:111]
	v_cvt_pk_bf16_f32 v119, v230, v231
	v_cvt_pk_bf16_f32 v112, v232, v233
	v_cvt_pk_bf16_f32 v113, v234, v235
	v_cvt_pk_bf16_f32 v114, v236, v237
	v_cvt_pk_bf16_f32 v115, v238, v239
	s_nop 0
	v_permlane32_swap_b32_e32 v204, v205
	v_permlane32_swap_b32_e32 v112, v114
	v_permlane32_swap_b32_e32 v113, v115
	v_cvt_pk_bf16_f32 v120, v206, v207
	v_cvt_pk_bf16_f32 v121, v240, v241
	v_cvt_pk_bf16_f32 v122, v242, v243
	v_cvt_pk_bf16_f32 v123, v244, v10
	v_cvt_pk_bf16_f32 v124, v11, v12
	v_cvt_pk_bf16_f32 v125, v13, v144
	v_cvt_pk_bf16_f32 v126, v145, v146
	v_cvt_pk_bf16_f32 v127, v6, v7
	v_permlane32_swap_b32_e32 v117, v119
	v_permlane32_swap_b32_e32 v120, v122
	v_permlane32_swap_b32_e32 v121, v123
	v_permlane32_swap_b32_e32 v124, v126
	v_permlane32_swap_b32_e32 v125, v127
	v_add_u32_e32 v230, s59, v175
	ds_read_b64_tr_b16 v[2:3], v230 offset:0
	ds_read_b64_tr_b16 v[4:5], v230 offset:0x800
	ds_read_b64_tr_b16 v[6:7], v230 offset:0x1000
	ds_read_b64_tr_b16 v[8:9], v230 offset:0x1800
	ds_read_b64_tr_b16 v[10:11], v230 offset:0x2000
	ds_read_b64_tr_b16 v[12:13], v230 offset:0x2800
	ds_read_b64_tr_b16 v[144:145], v230 offset:0x3000
	ds_read_b64_tr_b16 v[146:147], v230 offset:0x3800
	s_add_i32 s58, s58, 2
	s_waitcnt lgkmcnt(0)
; __device__ __forceinline__ void pv_d0(f32x16* o, int vb, bf16x8 pa0, bf16x8 pa1, bf16x8 pa2, bf16x8 pa3) {
;   s16x4 la[4], ha[4];
;   rd8<0>(la, ha, vb); WAITDEP(0, la, ha); mma4(o[0], la, ha, pa0, pa1, pa2, pa3);
;   rd8<1>(la, ha, vb); WAITDEP(0, la, ha); mma4(o[1], la, ha, pa0, pa1, pa2, pa3);
;   rd8<2>(la, ha, vb); WAITDEP(0, la, ha); mma4(o[2], la, ha, pa0, pa1, pa2, pa3);
;   rd8<3>(la, ha, vb); WAITDEP(0, la, ha); mma4(o[3], la, ha, pa0, pa1, pa2, pa3);
; }
; template <int MODE>
; __device__ __forceinline__ void attn_unit(bf16r* P0, const bf16r* __restrict__ PKV, int rowbase, int seqL, int h, int blk, float lam,
;                                           const float* __restrict__ subg, const float* __restrict__ tsrc, char* lds) {
;   constexpr int NQ = (MODE == 0) ? 4 : 8;
;   int tid_ = threadIdx.x; asm volatile("" : "+v"(tid_));
;   const int tid = tid_, wid = __builtin_amdgcn_readfirstlane(tid >> 6), lane = tid & 63, r32 = lane & 31, hi = lane >> 5;
;   float* ws = (float*)(lds + OFF_WS) + wid * 64; float* li_l = ws; float* al_l = ws + 32;
;   float* tb = (float*)(lds + OFF_TB);
;   int qrow, kcolB, tbase, NT, colbase, gr = 0, rs = 0, qc = 0, cmap = 0;
;   float bL = 0.f, bR = 0.f;
;   if constexpr (MODE == 0) {
;     cmap = wid >> 2; qrow = blk * 128 + (wid & 3) * 32; kcolB = cmap * 128; tbase = 0; NT = seqL / KVBLK; colbase = h * 128;
;     bL = tsrc[15 * 8 + h] * LOG2E; bR = tsrc[31 * 8 + h] * LOG2E;
;     { const int rel = tid - 256, n = rel < 0 ? -rel : rel;
;       int bk = n < 8 ? n : min(15, 8 + (31 - __clz((n * n) >> 6))); if (rel > 0) bk += 16;
;       tb[tid] = tsrc[bk * 8 + h] * LOG2E; }
;   } else {
;     const int rows = seqL / 64; qrow = blk * 256 + wid * 32; kcolB = 0; colbase = 1024 + h * 128; NT = 12;
;     const int rs0 = min(max(blk * 4 - 4, 0), rows - 8); tbase = min(rs0, rows - 12);
;     gr = blk * 4 + (wid >> 1); rs = min(max(gr - 4, 0), rows - 8); qc = (wid & 1) * 32 + r32;
;     for (int i = tid; i < 15 * 128; i += 512) { const int dr = i >> 7, dc = (i & 127) - 48; tb[i] = (dc >= 0 && dc < 31) ? tsrc[(h * 15 + dr) * 31 + dc] * LOG2E : 0.f; }
;   }
;   const bf16r* Qw = P0 + (size_t)(rowbase + qrow + r32) * LD + colbase + (MODE == 0 ? cmap * 64 : 0) + hi * 8;
;   const bf16r* Kh = PKV + (size_t)rowbase * LD + h * 128; const bf16r* Vh = Kh + 1024;
;   float m_reg = -1e30f, l_reg = 0; f32x16 o[4] = {};
	s_add_i32 s34, s36, 0
	v_mfma_f32_32x32x16_bf16 v[64:79], v[116:119], v[2:5], v[64:79]
	ds_read_b64_tr_b16 v[2:3], v230 offset:0x200
	ds_read_b64_tr_b16 v[4:5], v230 offset:0xa00
	ds_read_b64_tr_b16 v[206:207], v230 offset:0x1200
	ds_read_b64_tr_b16 v[208:209], v230 offset:0x1a00
	ds_read_b64_tr_b16 v[210:211], v230 offset:0x2200
	ds_read_b64_tr_b16 v[212:213], v230 offset:0x2a00
	ds_read_b64_tr_b16 v[214:215], v230 offset:0x3200
	v_mfma_f32_32x32x16_bf16 v[64:79], v[112:115], v[6:9], v[64:79]
	ds_read_b64_tr_b16 v[216:217], v230 offset:0x3a00
	s_min_i32 s35, s58, s39
	s_waitcnt lgkmcnt(0)
	s_cmp_ge_i32 s35, s56
	s_cselect_b32 s60, s57, 0
	s_add_i32 s60, s60, s35
	s_lshl_b32 s35, s60, 6
	v_mfma_f32_32x32x16_bf16 v[48:63], v[116:119], v[2:5], v[48:63]
	ds_read_b64_tr_b16 v[2:3], v230 offset:0x400
	ds_read_b64_tr_b16 v[4:5], v230 offset:0xc00
	ds_read_b64_tr_b16 v[6:7], v230 offset:0x1400
	ds_read_b64_tr_b16 v[8:9], v230 offset:0x1c00
	v_mfma_f32_32x32x16_bf16 v[64:79], v[120:123], v[10:13], v[64:79]
	ds_read_b64_tr_b16 v[10:11], v230 offset:0x2400
	ds_read_b64_tr_b16 v[12:13], v230 offset:0x2c00
	v_mfma_f32_32x32x16_bf16 v[48:63], v[112:115], v[206:209], v[48:63]
	ds_read_b64_tr_b16 v[206:207], v230 offset:0x3400
	ds_read_b64_tr_b16 v[208:209], v230 offset:0x3c00
	s_nop 0
	s_waitcnt lgkmcnt(0)
	ds_read_b64_tr_b16 v[218:219], v230 offset:0x600
	ds_read_b64_tr_b16 v[220:221], v230 offset:0xe00
	s_nop 0
	v_mfma_f32_32x32x16_bf16 v[32:47], v[116:119], v[2:5], v[32:47]
	s_lshl_b32 s98, s35, 12
	s_add_u32 s98, s30, s98
	s_addc_u32 s99, s31, 0
	v_mfma_f32_32x32x16_bf16 v[48:63], v[120:123], v[210:213], v[48:63]
	ds_read_b64_tr_b16 v[210:211], v230 offset:0x1600
	ds_read_b64_tr_b16 v[212:213], v230 offset:0x1e00
	ds_read_b64_tr_b16 v[222:223], v230 offset:0x2600
	ds_read_b64_tr_b16 v[224:225], v230 offset:0x2e00
	ds_read_b64_tr_b16 v[226:227], v230 offset:0x3600
	ds_read_b64_tr_b16 v[228:229], v230 offset:0x3e00
	v_mfma_f32_32x32x16_bf16 v[32:47], v[112:115], v[6:9], v[32:47]
	s_waitcnt lgkmcnt(0)
	s_waitcnt vmcnt(0)
	v_mfma_f32_32x32x16_bf16 v[48:63], v[124:127], v[214:217], v[48:63]
	global_load_dwordx4 v[6:9], v252, s[98:99] offset:2048
	s_nop 0
	global_load_dwordx4 v[2:5], v252, s[98:99]
	v_mfma_f32_32x32x16_bf16 v[64:79], v[124:127], v[144:147], v[64:79]
	v_mfma_f32_32x32x16_bf16 v[32:47], v[120:123], v[10:13], v[32:47]
	global_load_dwordx4 v[144:147], v253, s[98:99] offset:2048
	global_load_dwordx4 v[10:13], v253, s[98:99]
	v_add_u32_e32 v214, s34, v183
	ds_write_b128 v214, v[156:159]
	v_add_u32_e32 v156, s34, v189
	ds_write_b128 v156, v[160:163]
	v_add_u32_e32 v156, s34, v190
	ds_write_b128 v156, v[148:151] offset:16384
	v_mfma_f32_32x32x16_bf16 v[16:31], v[116:119], v[218:221], v[16:31]
	v_add_u32_e32 v148, s34, v191
	ds_write_b128 v148, v[152:155] offset:16384
	v_max_f32_e32 v148, v128, v129
	v_max3_f32 v148, v148, v130, v131
	v_max3_f32 v148, v148, v132, v133
	v_mfma_f32_32x32x16_bf16 v[16:31], v[112:115], v[210:213], v[16:31]
	v_max3_f32 v116, v148, v134, v135
	v_max3_f32 v116, v116, v136, v137
	v_max3_f32 v116, v116, v138, v139
	v_max3_f32 v116, v116, v140, v141
	v_max3_f32 v116, v116, v142, v143
	v_max3_f32 v116, v116, v96, v97
	v_max3_f32 v116, v116, v98, v99
	v_mfma_f32_32x32x16_bf16 v[16:31], v[120:123], v[222:225], v[16:31]
	v_max3_f32 v112, v116, v100, v101
	v_max3_f32 v112, v112, v102, v103
	v_max3_f32 v112, v112, v104, v105
	v_max3_f32 v112, v112, v106, v107
	v_max3_f32 v112, v112, v108, v109
	v_max3_f32 v112, v112, v110, v111
	v_mov_b32_e32 v113, v112
	v_mfma_f32_32x32x16_bf16 v[32:47], v[124:127], v[206:209], v[32:47]
	s_nop 0
	v_permlane32_swap_b32_e32 v112, v113
	v_max_f32_e32 v113, v112, v113
	v_cmp_ge_f32_e32 vcc, s49, v113
	s_cmp_eq_u64 vcc, exec
	v_mfma_f32_32x32x16_bf16 v[16:31], v[124:127], v[226:229], v[16:31]
	v_mov_b32_e32 v112, 1.0
	s_cbranch_scc0 .LBB0_230
	s_branch .LBB0_227
